# v112 + first 16 workgroups of XCD 5 also start on the FoX queue (112 FoX-first; relieves the only neighbouring pair of second-queue XCDs)
# speedup vs baseline: 1.0014x; 1.0014x over previous
; #define LAS __attribute__((address_space(3)))
;     LAS int* sitem = (LAS int*)(lds + ITEM_OFF);
;     constexpr int N_D = 256, N_B = 2048, N_A = 128, N_C = 128, N_ALL = N_D + N_B + N_A + N_C;
;     const int pref = ((__builtin_amdgcn_s_getreg((3 << 11) | 20) & 3u) != 0u) ? 1 : 0;
;     auto fetch = [&]() -> int {
;         auto q1 = [&](int i) -> int { return i < N_A + N_C ? N_D + N_B + i : N_D + (i - (N_A + N_C)); };
;         if (pref == 0) { int i = (int)atomicAdd(ctr, 1u); if (i < N_D) return i; i = (int)atomicAdd(ctr + 32, 1u); return i < N_ALL - N_D ? q1(i) : N_ALL; }
;         int i = (int)atomicAdd(ctr + 32, 1u); if (i < N_ALL - N_D) return q1(i); i = (int)atomicAdd(ctr, 1u); return i < N_D ? i : N_ALL; };
;     int nxt = 0;
;     if (threadIdx.x == 0) nxt = fetch();
.LBB0_112:
	v_readlane_b32 s0, v253, 49
	v_readlane_b32 s1, v253, 50
	s_lshl_b32 s0, s0, 1
	v_readlane_b32 s1, v253, 51
	s_add_i32 s0, s0, s1
	s_ashr_i32 s1, s0, 31
	v_readlane_b32 s20, v251, 1
	s_lshl_b64 s[0:1], s[0:1], 2
	v_readlane_b32 s22, v251, 3
	v_readlane_b32 s23, v251, 4
	s_add_u32 s0, s22, s0
	s_addc_u32 s1, s23, s1
	v_writelane_b32 v253, s0, 55
	v_mov_b32_e32 v180, 0
	v_readlane_b32 s21, v251, 2
	v_writelane_b32 v253, s1, 56
	s_getreg_b32 s0, hwreg(HW_REG_XCC_ID, 0, 4)
	s_lshr_b32 s1, 0x49, s0
	s_and_b32 s1, s1, 1
	v_readlane_b32 vcc_lo, v251, 0
	s_lshr_b32 vcc_lo, vcc_lo, 3
	s_cmp_lt_u32 vcc_lo, 16
	s_cselect_b32 vcc_lo, 1, 0
	s_cmp_eq_u32 s0, 5
	s_cselect_b32 vcc_hi, 1, 0
	s_and_b32 vcc_lo, vcc_lo, vcc_hi
	s_or_b32 s0, s1, vcc_lo
	s_cmp_eq_u32 s0, 0
	s_cselect_b64 s[0:1], -1, 0
	v_writelane_b32 v253, s0, 57
	v_readlane_b32 s24, v251, 5
	v_readlane_b32 s25, v251, 6
	v_writelane_b32 v253, s1, 58
	v_readlane_b32 s26, v251, 7
	v_readlane_b32 s27, v251, 8
	s_mov_b64 s[0:1], exec
	v_readlane_b32 s20, v251, 13
	v_readlane_b32 s21, v251, 14
	s_and_b64 s[20:21], s[0:1], s[20:21]
	s_mov_b64 exec, s[20:21]
	s_cbranch_execz .LBB0_131
	v_readlane_b32 s20, v253, 57
	v_readlane_b32 s21, v253, 58
	s_and_b64 vcc, exec, s[20:21]
	s_cbranch_vccz .LBB0_123
	s_mov_b64 s[22:23], exec
	v_mbcnt_lo_u32_b32 v0, s22, 0
	v_mbcnt_hi_u32_b32 v0, s23, v0
	v_cmp_eq_u32_e32 vcc, 0, v0
	s_and_saveexec_b64 s[20:21], vcc
	s_cbranch_execz .LBB0_116
	s_bcnt1_i32_b64 s22, s[22:23]
	v_mov_b32_e32 v2, s22
	v_readlane_b32 s22, v253, 55
	v_readlane_b32 s23, v253, 56
	s_nop 4
	global_atomic_add v2, v1, v2, s[22:23] offset:128 sc0
